# down-GEMM seam rows hand-written: all loads up front, 16-byte accesses, packed fp32 math (was 12 serial latency-bound trips)
# speedup vs baseline: 1.0097x; 1.0043x over previous
.LBB0_1105:
	s_cmp_lt_i32 s59, 32
	s_cbranch_scc1 .LBB0_1118
	s_and_b32 s24, s59, 3
	s_cmp_lg_u32 s24, 3
	s_cselect_b32 s26, 1, 0
	s_cmp_lg_u32 s24, 0
	s_cselect_b32 s27, 1, 0
	s_mov_b64 s[30:31], exec
	v_cmp_gt_u32_e32 vcc, 0x160, v0
	s_and_b64 exec, exec, vcc
	v_lshlrev_b32_e32 v228, 5, v0
	v_lshrrev_b32_e32 v232, 3, v0
	v_lshlrev_b32_e32 v232, 9, v232
	v_and_b32_e32 v229, 7, v0
	v_lshl_or_b32 v229, v229, 5, v232
	v_add_u32_e32 v230, 0x5800, v229
	v_add_u32_e32 v231, 0xb000, v229
	v_lshlrev_b32_e32 v233, 4, v0
	v_mov_b32_e32 v234, 0xbfb8aa3b
	v_mov_b32_e32 v235, 0xbfb8aa3b
	global_load_dwordx4 v[2:5], v228, s[8:9]
	global_load_dwordx4 v[6:9], v228, s[8:9] offset:16
	v_add_u32_e32 v232, 0x2c00, v228
	global_load_dwordx4 v[10:13], v232, s[8:9]
	global_load_dwordx4 v[14:17], v232, s[8:9] offset:16
	v_add_u32_e32 v232, 0x5800, v228
	global_load_dwordx4 v[18:21], v232, s[8:9]
	global_load_dwordx4 v[22:25], v232, s[8:9] offset:16
	v_add_u32_e32 v232, 0x8400, v228
	global_load_dwordx4 v[26:29], v232, s[8:9]
	global_load_dwordx4 v[30:33], v232, s[8:9] offset:16
	v_add_u32_e32 v232, 0xb000, v228
	global_load_dwordx4 v[34:37], v232, s[8:9]
	global_load_dwordx4 v[38:41], v232, s[8:9] offset:16
	v_add_u32_e32 v232, 0xdc00, v228
	global_load_dwordx4 v[42:45], v232, s[8:9]
	global_load_dwordx4 v[46:49], v232, s[8:9] offset:16
	global_load_dwordx4 v[50:53], v228, s[10:11]
	global_load_dwordx4 v[54:57], v228, s[10:11] offset:16
	v_add_u32_e32 v232, 0x2c00, v228
	global_load_dwordx4 v[58:61], v232, s[10:11]
	global_load_dwordx4 v[62:65], v232, s[10:11] offset:16
	s_cmp_eq_u32 s26, 0
	s_cbranch_scc1 .Lseam_p8_lb
	s_lshl_b32 s40, s59, 2
	s_add_i32 s40, s40, 2
	s_mul_hi_u32 s35, s40, 0x5800
	s_mul_i32 s34, s40, 0x5800
	s_add_u32 s34, s2, s34
	s_addc_u32 s35, s3, s35
	global_load_dwordx4 v[66:69], v229, s[34:35]
	global_load_dwordx4 v[70:73], v229, s[34:35] offset:16
	global_load_dwordx4 v[74:77], v229, s[34:35] offset:256
	global_load_dwordx4 v[78:81], v229, s[34:35] offset:272
	global_load_dwordx4 v[82:85], v230, s[34:35]
	global_load_dwordx4 v[86:89], v230, s[34:35] offset:16
	global_load_dwordx4 v[90:93], v230, s[34:35] offset:256
	global_load_dwordx4 v[94:97], v230, s[34:35] offset:272
	global_load_dwordx4 v[98:101], v231, s[34:35]
	global_load_dwordx4 v[102:105], v231, s[34:35] offset:16
	global_load_dwordx4 v[106:109], v231, s[34:35] offset:256
	global_load_dwordx4 v[110:113], v231, s[34:35] offset:272
.Lseam_p8_lb:
	s_cmp_eq_u32 s27, 0
	s_cbranch_scc1 .Lseam_p8_lt
	s_lshl_b32 s40, s59, 2
	s_add_i32 s40, s40, -1
	s_mul_hi_u32 s37, s40, 0x5800
	s_mul_i32 s36, s40, 0x5800
	s_add_u32 s36, s2, s36
	s_addc_u32 s37, s3, s37
	global_load_dwordx4 v[114:117], v229, s[36:37]
	global_load_dwordx4 v[118:121], v229, s[36:37] offset:16
	global_load_dwordx4 v[122:125], v229, s[36:37] offset:256
	global_load_dwordx4 v[126:129], v229, s[36:37] offset:272
	global_load_dwordx4 v[168:171], v230, s[36:37]
	global_load_dwordx4 v[172:175], v230, s[36:37] offset:16
	global_load_dwordx4 v[176:179], v230, s[36:37] offset:256
	global_load_dwordx4 v[180:183], v230, s[36:37] offset:272
	global_load_dwordx4 v[184:187], v231, s[36:37]
	global_load_dwordx4 v[188:191], v231, s[36:37] offset:16
	global_load_dwordx4 v[192:195], v231, s[36:37] offset:256
	global_load_dwordx4 v[196:199], v231, s[36:37] offset:272
.Lseam_p8_lt:
	s_waitcnt vmcnt(0)
	s_cmp_eq_u32 s26, 0
	s_cbranch_scc1 .Lseam_p8_cb
	s_lshl_b32 s40, s59, 8
	s_add_i32 s40, s40, 255
	s_mul_hi_u32 s39, s40, 0x1600
	s_mul_i32 s38, s40, 0x1600
	s_add_u32 s38, s12, s38
	s_addc_u32 s39, s13, s39
	v_pk_fma_f32 v[200:201], v[2:3], v[66:67], v[50:51]
	v_pk_fma_f32 v[210:211], v[10:11], v[74:75], v[58:59]
	v_pk_fma_f32 v[202:203], v[4:5], v[68:69], v[52:53]
	v_pk_fma_f32 v[212:213], v[12:13], v[76:77], v[60:61]
	v_pk_fma_f32 v[204:205], v[6:7], v[70:71], v[54:55]
	v_pk_fma_f32 v[214:215], v[14:15], v[78:79], v[62:63]
	v_pk_fma_f32 v[206:207], v[8:9], v[72:73], v[56:57]
	v_pk_fma_f32 v[216:217], v[16:17], v[80:81], v[64:65]
	v_pk_fma_f32 v[200:201], v[18:19], v[82:83], v[200:201]
	v_pk_fma_f32 v[210:211], v[26:27], v[90:91], v[210:211]
	v_pk_fma_f32 v[202:203], v[20:21], v[84:85], v[202:203]
	v_pk_fma_f32 v[212:213], v[28:29], v[92:93], v[212:213]
	v_pk_fma_f32 v[204:205], v[22:23], v[86:87], v[204:205]
	v_pk_fma_f32 v[214:215], v[30:31], v[94:95], v[214:215]
	v_pk_fma_f32 v[206:207], v[24:25], v[88:89], v[206:207]
	v_pk_fma_f32 v[216:217], v[32:33], v[96:97], v[216:217]
	v_pk_fma_f32 v[200:201], v[34:35], v[98:99], v[200:201]
	v_pk_fma_f32 v[210:211], v[42:43], v[106:107], v[210:211]
	v_pk_fma_f32 v[202:203], v[36:37], v[100:101], v[202:203]
	v_pk_fma_f32 v[212:213], v[44:45], v[108:109], v[212:213]
	v_pk_fma_f32 v[204:205], v[38:39], v[102:103], v[204:205]
	v_pk_fma_f32 v[214:215], v[46:47], v[110:111], v[214:215]
	v_pk_fma_f32 v[206:207], v[40:41], v[104:105], v[206:207]
	v_pk_fma_f32 v[216:217], v[48:49], v[112:113], v[216:217]
	v_pk_mul_f32 v[218:219], v[234:235], v[200:201]
	v_pk_mul_f32 v[220:221], v[234:235], v[202:203]
	v_pk_mul_f32 v[222:223], v[234:235], v[204:205]
	v_pk_mul_f32 v[224:225], v[234:235], v[206:207]
	v_exp_f32_e32 v218, v218
	v_exp_f32_e32 v219, v219
	v_exp_f32_e32 v220, v220
	v_exp_f32_e32 v221, v221
	v_exp_f32_e32 v222, v222
	v_exp_f32_e32 v223, v223
	v_exp_f32_e32 v224, v224
	v_exp_f32_e32 v225, v225
	v_pk_add_f32 v[218:219], v[218:219], 1.0 op_sel_hi:[1,0]
	v_pk_add_f32 v[220:221], v[220:221], 1.0 op_sel_hi:[1,0]
	v_pk_add_f32 v[222:223], v[222:223], 1.0 op_sel_hi:[1,0]
	v_pk_add_f32 v[224:225], v[224:225], 1.0 op_sel_hi:[1,0]
	v_rcp_f32_e32 v218, v218
	v_rcp_f32_e32 v219, v219
	v_rcp_f32_e32 v220, v220
	v_rcp_f32_e32 v221, v221
	v_rcp_f32_e32 v222, v222
	v_rcp_f32_e32 v223, v223
	v_rcp_f32_e32 v224, v224
	v_rcp_f32_e32 v225, v225
	v_pk_mul_f32 v[218:219], v[200:201], v[218:219]
	v_pk_mul_f32 v[220:221], v[202:203], v[220:221]
	v_pk_mul_f32 v[222:223], v[204:205], v[222:223]
	v_pk_mul_f32 v[224:225], v[206:207], v[224:225]
	v_pk_mul_f32 v[218:219], v[218:219], v[210:211]
	v_pk_mul_f32 v[220:221], v[220:221], v[212:213]
	v_pk_mul_f32 v[222:223], v[222:223], v[214:215]
	v_pk_mul_f32 v[224:225], v[224:225], v[216:217]
	v_cvt_pk_bf16_f32 v236, v218, v219
	v_cvt_pk_bf16_f32 v237, v220, v221
	v_cvt_pk_bf16_f32 v238, v222, v223
	v_cvt_pk_bf16_f32 v239, v224, v225
	global_store_dwordx4 v233, v[236:239], s[38:39]
.Lseam_p8_cb:
	s_cmp_eq_u32 s27, 0
	s_cbranch_scc1 .Lseam_p8_ct
	s_lshl_b32 s40, s59, 8
	s_mul_hi_u32 s39, s40, 0x1600
	s_mul_i32 s38, s40, 0x1600
	s_add_u32 s38, s12, s38
	s_addc_u32 s39, s13, s39
	v_pk_fma_f32 v[200:201], v[2:3], v[114:115], v[50:51]
	v_pk_fma_f32 v[210:211], v[10:11], v[122:123], v[58:59]
	v_pk_fma_f32 v[202:203], v[4:5], v[116:117], v[52:53]
	v_pk_fma_f32 v[212:213], v[12:13], v[124:125], v[60:61]
	v_pk_fma_f32 v[204:205], v[6:7], v[118:119], v[54:55]
	v_pk_fma_f32 v[214:215], v[14:15], v[126:127], v[62:63]
	v_pk_fma_f32 v[206:207], v[8:9], v[120:121], v[56:57]
	v_pk_fma_f32 v[216:217], v[16:17], v[128:129], v[64:65]
	v_pk_fma_f32 v[200:201], v[18:19], v[168:169], v[200:201]
	v_pk_fma_f32 v[210:211], v[26:27], v[176:177], v[210:211]
	v_pk_fma_f32 v[202:203], v[20:21], v[170:171], v[202:203]
	v_pk_fma_f32 v[212:213], v[28:29], v[178:179], v[212:213]
	v_pk_fma_f32 v[204:205], v[22:23], v[172:173], v[204:205]
	v_pk_fma_f32 v[214:215], v[30:31], v[180:181], v[214:215]
	v_pk_fma_f32 v[206:207], v[24:25], v[174:175], v[206:207]
	v_pk_fma_f32 v[216:217], v[32:33], v[182:183], v[216:217]
	v_pk_fma_f32 v[200:201], v[34:35], v[184:185], v[200:201]
	v_pk_fma_f32 v[210:211], v[42:43], v[192:193], v[210:211]
	v_pk_fma_f32 v[202:203], v[36:37], v[186:187], v[202:203]
	v_pk_fma_f32 v[212:213], v[44:45], v[194:195], v[212:213]
	v_pk_fma_f32 v[204:205], v[38:39], v[188:189], v[204:205]
	v_pk_fma_f32 v[214:215], v[46:47], v[196:197], v[214:215]
	v_pk_fma_f32 v[206:207], v[40:41], v[190:191], v[206:207]
	v_pk_fma_f32 v[216:217], v[48:49], v[198:199], v[216:217]
	v_pk_mul_f32 v[218:219], v[234:235], v[200:201]
	v_pk_mul_f32 v[220:221], v[234:235], v[202:203]
	v_pk_mul_f32 v[222:223], v[234:235], v[204:205]
	v_pk_mul_f32 v[224:225], v[234:235], v[206:207]
	v_exp_f32_e32 v218, v218
	v_exp_f32_e32 v219, v219
	v_exp_f32_e32 v220, v220
	v_exp_f32_e32 v221, v221
	v_exp_f32_e32 v222, v222
	v_exp_f32_e32 v223, v223
	v_exp_f32_e32 v224, v224
	v_exp_f32_e32 v225, v225
	v_pk_add_f32 v[218:219], v[218:219], 1.0 op_sel_hi:[1,0]
	v_pk_add_f32 v[220:221], v[220:221], 1.0 op_sel_hi:[1,0]
	v_pk_add_f32 v[222:223], v[222:223], 1.0 op_sel_hi:[1,0]
	v_pk_add_f32 v[224:225], v[224:225], 1.0 op_sel_hi:[1,0]
	v_rcp_f32_e32 v218, v218
	v_rcp_f32_e32 v219, v219
	v_rcp_f32_e32 v220, v220
	v_rcp_f32_e32 v221, v221
	v_rcp_f32_e32 v222, v222
	v_rcp_f32_e32 v223, v223
	v_rcp_f32_e32 v224, v224
	v_rcp_f32_e32 v225, v225
	v_pk_mul_f32 v[218:219], v[200:201], v[218:219]
	v_pk_mul_f32 v[220:221], v[202:203], v[220:221]
	v_pk_mul_f32 v[222:223], v[204:205], v[222:223]
	v_pk_mul_f32 v[224:225], v[206:207], v[224:225]
	v_pk_mul_f32 v[218:219], v[218:219], v[210:211]
	v_pk_mul_f32 v[220:221], v[220:221], v[212:213]
	v_pk_mul_f32 v[222:223], v[222:223], v[214:215]
	v_pk_mul_f32 v[224:225], v[224:225], v[216:217]
	v_cvt_pk_bf16_f32 v236, v218, v219
	v_cvt_pk_bf16_f32 v237, v220, v221
	v_cvt_pk_bf16_f32 v238, v222, v223
	v_cvt_pk_bf16_f32 v239, v224, v225
	global_store_dwordx4 v233, v[236:239], s[38:39]
.Lseam_p8_ct:
	s_mov_b64 exec, s[30:31]
	s_waitcnt vmcnt(0)
	s_barrier

.LBB0_1891:
	s_cmp_lt_i32 s56, 32
	s_cbranch_scc1 .LBB0_1904
	s_and_b32 s24, s56, 3
	s_cmp_lg_u32 s24, 3
	s_cselect_b32 s26, 1, 0
	s_cmp_lg_u32 s24, 0
	s_cselect_b32 s27, 1, 0
	s_mov_b64 s[30:31], exec
	v_cmp_gt_u32_e32 vcc, 0x160, v0
	s_and_b64 exec, exec, vcc
	v_lshlrev_b32_e32 v228, 5, v0
	v_lshrrev_b32_e32 v232, 3, v0
	v_lshlrev_b32_e32 v232, 9, v232
	v_and_b32_e32 v229, 7, v0
	v_lshl_or_b32 v229, v229, 5, v232
	v_add_u32_e32 v230, 0x5800, v229
	v_add_u32_e32 v231, 0xb000, v229
	v_lshlrev_b32_e32 v233, 4, v0
	v_mov_b32_e32 v234, 0xbfb8aa3b
	v_mov_b32_e32 v235, 0xbfb8aa3b
	v_add_u32_e32 v232, 0x10800, v228
	global_load_dwordx4 v[2:5], v232, s[8:9]
	global_load_dwordx4 v[6:9], v232, s[8:9] offset:16
	v_add_u32_e32 v232, 0x13400, v228
	global_load_dwordx4 v[10:13], v232, s[8:9]
	global_load_dwordx4 v[14:17], v232, s[8:9] offset:16
	v_add_u32_e32 v232, 0x16000, v228
	global_load_dwordx4 v[18:21], v232, s[8:9]
	global_load_dwordx4 v[22:25], v232, s[8:9] offset:16
	v_add_u32_e32 v232, 0x18c00, v228
	global_load_dwordx4 v[26:29], v232, s[8:9]
	global_load_dwordx4 v[30:33], v232, s[8:9] offset:16
	v_add_u32_e32 v232, 0x1b800, v228
	global_load_dwordx4 v[34:37], v232, s[8:9]
	global_load_dwordx4 v[38:41], v232, s[8:9] offset:16
	v_add_u32_e32 v232, 0x1e400, v228
	global_load_dwordx4 v[42:45], v232, s[8:9]
	global_load_dwordx4 v[46:49], v232, s[8:9] offset:16
	v_add_u32_e32 v232, 0x5800, v228
	global_load_dwordx4 v[50:53], v232, s[10:11]
	global_load_dwordx4 v[54:57], v232, s[10:11] offset:16
	v_add_u32_e32 v232, 0x8400, v228
	global_load_dwordx4 v[58:61], v232, s[10:11]
	global_load_dwordx4 v[62:65], v232, s[10:11] offset:16
	s_cmp_eq_u32 s26, 0
	s_cbranch_scc1 .Lseam_p15_lb
	s_lshl_b32 s40, s56, 2
	s_add_i32 s40, s40, 2
	s_mul_hi_u32 s35, s40, 0x5800
	s_mul_i32 s34, s40, 0x5800
	s_add_u32 s34, s2, s34
	s_addc_u32 s35, s3, s35
	global_load_dwordx4 v[66:69], v229, s[34:35]
	global_load_dwordx4 v[70:73], v229, s[34:35] offset:16
	global_load_dwordx4 v[74:77], v229, s[34:35] offset:256
	global_load_dwordx4 v[78:81], v229, s[34:35] offset:272
	global_load_dwordx4 v[82:85], v230, s[34:35]
	global_load_dwordx4 v[86:89], v230, s[34:35] offset:16
	global_load_dwordx4 v[90:93], v230, s[34:35] offset:256
	global_load_dwordx4 v[94:97], v230, s[34:35] offset:272
	global_load_dwordx4 v[98:101], v231, s[34:35]
	global_load_dwordx4 v[102:105], v231, s[34:35] offset:16
	global_load_dwordx4 v[106:109], v231, s[34:35] offset:256
	global_load_dwordx4 v[110:113], v231, s[34:35] offset:272
.Lseam_p15_lb:
	s_cmp_eq_u32 s27, 0
	s_cbranch_scc1 .Lseam_p15_lt
	s_lshl_b32 s40, s56, 2
	s_add_i32 s40, s40, -1
	s_mul_hi_u32 s37, s40, 0x5800
	s_mul_i32 s36, s40, 0x5800
	s_add_u32 s36, s2, s36
	s_addc_u32 s37, s3, s37
	global_load_dwordx4 v[114:117], v229, s[36:37]
	global_load_dwordx4 v[118:121], v229, s[36:37] offset:16
	global_load_dwordx4 v[122:125], v229, s[36:37] offset:256
	global_load_dwordx4 v[126:129], v229, s[36:37] offset:272
	global_load_dwordx4 v[168:171], v230, s[36:37]
	global_load_dwordx4 v[172:175], v230, s[36:37] offset:16
	global_load_dwordx4 v[176:179], v230, s[36:37] offset:256
	global_load_dwordx4 v[180:183], v230, s[36:37] offset:272
	global_load_dwordx4 v[184:187], v231, s[36:37]
	global_load_dwordx4 v[188:191], v231, s[36:37] offset:16
	global_load_dwordx4 v[192:195], v231, s[36:37] offset:256
	global_load_dwordx4 v[196:199], v231, s[36:37] offset:272
.Lseam_p15_lt:
	s_waitcnt vmcnt(0)
	s_cmp_eq_u32 s26, 0
	s_cbranch_scc1 .Lseam_p15_cb
	s_lshl_b32 s40, s56, 8
	s_add_i32 s40, s40, 255
	s_mul_hi_u32 s39, s40, 0x1600
	s_mul_i32 s38, s40, 0x1600
	s_add_u32 s38, s12, s38
	s_addc_u32 s39, s13, s39
	v_pk_fma_f32 v[200:201], v[2:3], v[66:67], v[50:51]
	v_pk_fma_f32 v[210:211], v[10:11], v[74:75], v[58:59]
	v_pk_fma_f32 v[202:203], v[4:5], v[68:69], v[52:53]
	v_pk_fma_f32 v[212:213], v[12:13], v[76:77], v[60:61]
	v_pk_fma_f32 v[204:205], v[6:7], v[70:71], v[54:55]
	v_pk_fma_f32 v[214:215], v[14:15], v[78:79], v[62:63]
	v_pk_fma_f32 v[206:207], v[8:9], v[72:73], v[56:57]
	v_pk_fma_f32 v[216:217], v[16:17], v[80:81], v[64:65]
	v_pk_fma_f32 v[200:201], v[18:19], v[82:83], v[200:201]
	v_pk_fma_f32 v[210:211], v[26:27], v[90:91], v[210:211]
	v_pk_fma_f32 v[202:203], v[20:21], v[84:85], v[202:203]
	v_pk_fma_f32 v[212:213], v[28:29], v[92:93], v[212:213]
	v_pk_fma_f32 v[204:205], v[22:23], v[86:87], v[204:205]
	v_pk_fma_f32 v[214:215], v[30:31], v[94:95], v[214:215]
	v_pk_fma_f32 v[206:207], v[24:25], v[88:89], v[206:207]
	v_pk_fma_f32 v[216:217], v[32:33], v[96:97], v[216:217]
	v_pk_fma_f32 v[200:201], v[34:35], v[98:99], v[200:201]
	v_pk_fma_f32 v[210:211], v[42:43], v[106:107], v[210:211]
	v_pk_fma_f32 v[202:203], v[36:37], v[100:101], v[202:203]
	v_pk_fma_f32 v[212:213], v[44:45], v[108:109], v[212:213]
	v_pk_fma_f32 v[204:205], v[38:39], v[102:103], v[204:205]
	v_pk_fma_f32 v[214:215], v[46:47], v[110:111], v[214:215]
	v_pk_fma_f32 v[206:207], v[40:41], v[104:105], v[206:207]
	v_pk_fma_f32 v[216:217], v[48:49], v[112:113], v[216:217]
	v_pk_mul_f32 v[218:219], v[234:235], v[200:201]
	v_pk_mul_f32 v[220:221], v[234:235], v[202:203]
	v_pk_mul_f32 v[222:223], v[234:235], v[204:205]
	v_pk_mul_f32 v[224:225], v[234:235], v[206:207]
	v_exp_f32_e32 v218, v218
	v_exp_f32_e32 v219, v219
	v_exp_f32_e32 v220, v220
	v_exp_f32_e32 v221, v221
	v_exp_f32_e32 v222, v222
	v_exp_f32_e32 v223, v223
	v_exp_f32_e32 v224, v224
	v_exp_f32_e32 v225, v225
	v_pk_add_f32 v[218:219], v[218:219], 1.0 op_sel_hi:[1,0]
	v_pk_add_f32 v[220:221], v[220:221], 1.0 op_sel_hi:[1,0]
	v_pk_add_f32 v[222:223], v[222:223], 1.0 op_sel_hi:[1,0]
	v_pk_add_f32 v[224:225], v[224:225], 1.0 op_sel_hi:[1,0]
	v_rcp_f32_e32 v218, v218
	v_rcp_f32_e32 v219, v219
	v_rcp_f32_e32 v220, v220
	v_rcp_f32_e32 v221, v221
	v_rcp_f32_e32 v222, v222
	v_rcp_f32_e32 v223, v223
	v_rcp_f32_e32 v224, v224
	v_rcp_f32_e32 v225, v225
	v_pk_mul_f32 v[218:219], v[200:201], v[218:219]
	v_pk_mul_f32 v[220:221], v[202:203], v[220:221]
	v_pk_mul_f32 v[222:223], v[204:205], v[222:223]
	v_pk_mul_f32 v[224:225], v[206:207], v[224:225]
	v_pk_mul_f32 v[218:219], v[218:219], v[210:211]
	v_pk_mul_f32 v[220:221], v[220:221], v[212:213]
	v_pk_mul_f32 v[222:223], v[222:223], v[214:215]
	v_pk_mul_f32 v[224:225], v[224:225], v[216:217]
	v_cvt_pk_bf16_f32 v236, v218, v219
	v_cvt_pk_bf16_f32 v237, v220, v221
	v_cvt_pk_bf16_f32 v238, v222, v223
	v_cvt_pk_bf16_f32 v239, v224, v225
	global_store_dwordx4 v233, v[236:239], s[38:39]
.Lseam_p15_cb:
	s_cmp_eq_u32 s27, 0
	s_cbranch_scc1 .Lseam_p15_ct
	s_lshl_b32 s40, s56, 8
	s_mul_hi_u32 s39, s40, 0x1600
	s_mul_i32 s38, s40, 0x1600
	s_add_u32 s38, s12, s38
	s_addc_u32 s39, s13, s39
	v_pk_fma_f32 v[200:201], v[2:3], v[114:115], v[50:51]
	v_pk_fma_f32 v[210:211], v[10:11], v[122:123], v[58:59]
	v_pk_fma_f32 v[202:203], v[4:5], v[116:117], v[52:53]
	v_pk_fma_f32 v[212:213], v[12:13], v[124:125], v[60:61]
	v_pk_fma_f32 v[204:205], v[6:7], v[118:119], v[54:55]
	v_pk_fma_f32 v[214:215], v[14:15], v[126:127], v[62:63]
	v_pk_fma_f32 v[206:207], v[8:9], v[120:121], v[56:57]
	v_pk_fma_f32 v[216:217], v[16:17], v[128:129], v[64:65]
	v_pk_fma_f32 v[200:201], v[18:19], v[168:169], v[200:201]
	v_pk_fma_f32 v[210:211], v[26:27], v[176:177], v[210:211]
	v_pk_fma_f32 v[202:203], v[20:21], v[170:171], v[202:203]
	v_pk_fma_f32 v[212:213], v[28:29], v[178:179], v[212:213]
	v_pk_fma_f32 v[204:205], v[22:23], v[172:173], v[204:205]
	v_pk_fma_f32 v[214:215], v[30:31], v[180:181], v[214:215]
	v_pk_fma_f32 v[206:207], v[24:25], v[174:175], v[206:207]
	v_pk_fma_f32 v[216:217], v[32:33], v[182:183], v[216:217]
	v_pk_fma_f32 v[200:201], v[34:35], v[184:185], v[200:201]
	v_pk_fma_f32 v[210:211], v[42:43], v[192:193], v[210:211]
	v_pk_fma_f32 v[202:203], v[36:37], v[186:187], v[202:203]
	v_pk_fma_f32 v[212:213], v[44:45], v[194:195], v[212:213]
	v_pk_fma_f32 v[204:205], v[38:39], v[188:189], v[204:205]
	v_pk_fma_f32 v[214:215], v[46:47], v[196:197], v[214:215]
	v_pk_fma_f32 v[206:207], v[40:41], v[190:191], v[206:207]
	v_pk_fma_f32 v[216:217], v[48:49], v[198:199], v[216:217]
	v_pk_mul_f32 v[218:219], v[234:235], v[200:201]
	v_pk_mul_f32 v[220:221], v[234:235], v[202:203]
	v_pk_mul_f32 v[222:223], v[234:235], v[204:205]
	v_pk_mul_f32 v[224:225], v[234:235], v[206:207]
	v_exp_f32_e32 v218, v218
	v_exp_f32_e32 v219, v219
	v_exp_f32_e32 v220, v220
	v_exp_f32_e32 v221, v221
	v_exp_f32_e32 v222, v222
	v_exp_f32_e32 v223, v223
	v_exp_f32_e32 v224, v224
	v_exp_f32_e32 v225, v225
	v_pk_add_f32 v[218:219], v[218:219], 1.0 op_sel_hi:[1,0]
	v_pk_add_f32 v[220:221], v[220:221], 1.0 op_sel_hi:[1,0]
	v_pk_add_f32 v[222:223], v[222:223], 1.0 op_sel_hi:[1,0]
	v_pk_add_f32 v[224:225], v[224:225], 1.0 op_sel_hi:[1,0]
	v_rcp_f32_e32 v218, v218
	v_rcp_f32_e32 v219, v219
	v_rcp_f32_e32 v220, v220
	v_rcp_f32_e32 v221, v221
	v_rcp_f32_e32 v222, v222
	v_rcp_f32_e32 v223, v223
	v_rcp_f32_e32 v224, v224
	v_rcp_f32_e32 v225, v225
	v_pk_mul_f32 v[218:219], v[200:201], v[218:219]
	v_pk_mul_f32 v[220:221], v[202:203], v[220:221]
	v_pk_mul_f32 v[222:223], v[204:205], v[222:223]
	v_pk_mul_f32 v[224:225], v[206:207], v[224:225]
	v_pk_mul_f32 v[218:219], v[218:219], v[210:211]
	v_pk_mul_f32 v[220:221], v[220:221], v[212:213]
	v_pk_mul_f32 v[222:223], v[222:223], v[214:215]
	v_pk_mul_f32 v[224:225], v[224:225], v[216:217]
	v_cvt_pk_bf16_f32 v236, v218, v219
	v_cvt_pk_bf16_f32 v237, v220, v221
	v_cvt_pk_bf16_f32 v238, v222, v223
	v_cvt_pk_bf16_f32 v239, v224, v225
	global_store_dwordx4 v233, v[236:239], s[38:39]
